# combo: v94 + attention unit-top hoists (key tile 0 + gates) + static prio raise for attention waves 4-7 + prep next-row touch
# speedup vs baseline: 1.0045x; 1.0024x over previous
.LBB0_514:
	v_and_b32_e32 v0, 0x1fff, v64
	v_cmp_ne_u32_e32 vcc, s18, v0
	v_lshl_add_u64 v[20:21], s[66:67], 0, v[76:77]
	v_mov_b32_e32 v1, s49
	v_cndmask_b32_e64 v0, 0, 1, vcc
	global_load_dwordx4 v[44:47], v[20:21], off
	global_load_dwordx4 v[40:43], v[20:21], off offset:16
	v_lshl_add_u64 v[0:1], v[64:65], 0, v[0:1]
	s_mov_b64 s[8:9], 0x2000000
	v_lshlrev_b64 v[0:1], 11, v[0:1]
	v_lshl_add_u64 v[2:3], v[20:21], 0, s[8:9]
	v_lshl_add_u64 v[0:1], v[72:73], 0, v[0:1]
	global_load_dwordx4 v[12:15], v[2:3], off offset:16
	global_load_dwordx4 v[52:55], v[0:1], off
	global_load_dwordx4 v[48:51], v[0:1], off offset:16
	global_load_dwordx4 v[16:19], v[66:67], off
	global_load_dwordx4 v[8:11], v[66:67], off offset:16
	global_load_dwordx4 v[4:7], v[66:67], off offset:32
	s_nop 0
	global_load_dwordx4 v[0:3], v[66:67], off offset:48
	s_brev_b32 s0, 64
	v_add_co_u32_e32 v20, vcc, s0, v20
	v_lshl_add_u64 v[24:25], s[66:67], 0, v[78:79]
	s_nop 0
	v_addc_co_u32_e32 v21, vcc, 0, v21, vcc
	global_load_dwordx4 v[20:23], v[20:21], off
	v_lshl_add_u64 v[26:27], v[24:25], 0, s[8:9]
	v_add_co_u32_e32 v24, vcc, s0, v24
	global_load_dwordx4 v[28:31], v[26:27], off offset:16
	s_nop 0
	v_addc_co_u32_e32 v25, vcc, 0, v25, vcc
	global_load_dwordx4 v[24:27], v[24:25], off
	s_nop 0
	global_load_dwordx4 v[36:39], v[68:69], off
	global_load_dwordx4 v[32:35], v[68:69], off offset:16
	global_load_dwordx4 v[56:59], v[68:69], off offset:32
	global_load_dwordx4 v[60:63], v[68:69], off offset:48
	s_waitcnt vmcnt(15)
	v_lshlrev_b32_e32 v121, 16, v47
	v_and_b32_e32 v146, 0xffff0000, v47
	v_lshlrev_b32_e32 v125, 16, v46
	s_waitcnt vmcnt(12)
	v_and_b32_e32 v47, 0xffff0000, v52
	v_and_b32_e32 v123, 0xffff0000, v46
	v_lshlrev_b32_e32 v46, 16, v52
	s_waitcnt vmcnt(10)
	v_mul_f32_e32 v92, v17, v47
	v_lshlrev_b32_e32 v52, 16, v53
	v_mul_f32_e32 v46, v16, v46
	v_mul_f32_e32 v47, v92, v92
	v_and_b32_e32 v53, 0xffff0000, v53
	v_mul_f32_e32 v93, v18, v52
	v_fmac_f32_e32 v47, v46, v46
	v_lshlrev_b32_e32 v80, 16, v54
	v_mul_f32_e32 v94, v19, v53
	v_fmac_f32_e32 v47, v93, v93
	v_and_b32_e32 v54, 0xffff0000, v54
	s_waitcnt vmcnt(9)
	v_mul_f32_e32 v95, v8, v80
	v_fmac_f32_e32 v47, v94, v94
	v_lshlrev_b32_e32 v82, 16, v55
	v_mul_f32_e32 v96, v9, v54
	v_fmac_f32_e32 v47, v95, v95
	v_and_b32_e32 v55, 0xffff0000, v55
	v_mul_f32_e32 v97, v10, v82
	v_fmac_f32_e32 v47, v96, v96
	v_lshlrev_b32_e32 v83, 16, v48
	v_mul_f32_e32 v98, v11, v55
	v_fmac_f32_e32 v47, v97, v97
	v_lshlrev_b32_e32 v119, 16, v40
	v_and_b32_e32 v117, 0xffff0000, v40
	v_lshlrev_b32_e32 v115, 16, v41
	v_and_b32_e32 v111, 0xffff0000, v41
	v_and_b32_e32 v48, 0xffff0000, v48
	v_lshlrev_b32_e32 v40, 16, v49
	v_and_b32_e32 v41, 0xffff0000, v49
	s_waitcnt vmcnt(8)
	v_mul_f32_e32 v100, v4, v83
	v_fmac_f32_e32 v47, v98, v98
	v_mul_f32_e32 v101, v5, v48
	v_pk_mul_f32 v[90:91], v[6:7], v[40:41]
	v_fmac_f32_e32 v47, v100, v100
	v_lshlrev_b32_e32 v109, 16, v42
	v_and_b32_e32 v105, 0xffff0000, v42
	v_lshlrev_b32_e32 v99, 16, v43
	v_and_b32_e32 v85, 0xffff0000, v43
	v_lshlrev_b32_e32 v42, 16, v50
	v_and_b32_e32 v43, 0xffff0000, v50
	v_pk_mul_f32 v[40:41], v[90:91], v[90:91]
	v_fmac_f32_e32 v47, v101, v101
	s_waitcnt vmcnt(7)
	v_pk_mul_f32 v[88:89], v[0:1], v[42:43]
	v_add_f32_e32 v40, v47, v40
	v_lshlrev_b32_e32 v145, 16, v44
	v_and_b32_e32 v144, 0xffff0000, v44
	v_lshlrev_b32_e32 v143, 16, v45
	v_and_b32_e32 v142, 0xffff0000, v45
	v_lshlrev_b32_e32 v44, 16, v51
	v_and_b32_e32 v45, 0xffff0000, v51
	v_pk_mul_f32 v[42:43], v[88:89], v[88:89]
	v_add_f32_e32 v40, v40, v41
	v_pk_mul_f32 v[86:87], v[2:3], v[44:45]
	v_add_f32_e32 v40, v40, v42
	v_pk_mul_f32 v[44:45], v[86:87], v[86:87]
	v_add_f32_e32 v40, v40, v43
	v_add_f32_e32 v40, v40, v44
	v_add_f32_e32 v40, v40, v45
	s_waitcnt vmcnt(4)
	v_lshlrev_b32_e32 v162, 16, v24
	v_lshlrev_b32_e32 v163, 16, v20
	v_add_f32_dpp v40, v40, v40 quad_perm:[1,0,3,2] row_mask:0xf bank_mask:0xf bound_ctrl:1
	v_and_b32_e32 v165, 0xffff0000, v20
	v_and_b32_e32 v164, 0xffff0000, v24
	v_add_f32_dpp v40, v40, v40 quad_perm:[2,3,0,1] row_mask:0xf bank_mask:0xf bound_ctrl:1
	v_max_f32_e32 v40, 0x179abe15, v40
	v_rsq_f32_e32 v147, v40
	v_lshlrev_b32_e32 v166, 16, v25
	v_mov_b32_e32 v190, v17
	v_mov_b32_e32 v212, v163
	v_mul_f32_e32 v84, v46, v147
	global_load_dwordx4 v[40:43], v[70:71], off offset:48
	global_load_dwordx4 v[44:47], v[70:71], off offset:32
	global_load_dwordx4 v[48:51], v[70:71], off offset:16
	global_load_dwordx4 v[52:55], v[70:71], off
	s_mov_b64 s[98:99], 0x2000000
	v_lshl_add_u64 v[214:215], v[76:77], 0, s[24:25]
	v_lshl_add_u64 v[216:217], v[78:79], 0, s[24:25]
	v_lshl_add_u64 v[214:215], v[214:215], 0, s[66:67]
	v_lshl_add_u64 v[216:217], v[216:217], 0, s[66:67]
	v_lshl_add_u64 v[218:219], v[214:215], 0, s[98:99]
	v_lshl_add_u64 v[216:217], v[216:217], 0, s[98:99]
	global_load_dword v220, v[214:215], off
	global_load_dword v221, v[218:219], off
	global_load_dword v222, v[218:219], off offset:2048
	global_load_dword v223, v[216:217], off
	v_mul_f32_e32 v110, v98, v147
	v_mul_f32_e32 v98, v90, v147
	v_mul_f32_e32 v90, v91, v147
	v_add_f32_e32 v91, -1.0, v162
	v_mov_b32_e32 v17, v91
	s_waitcnt vmcnt(11)
	v_mov_b32_e32 v213, v36
	v_mul_f32_e32 v114, v92, v147
	v_mul_f32_e32 v116, v93, v147
	v_mul_f32_e32 v124, v97, v147
	v_lshlrev_b32_e32 v103, 16, v14
	v_and_b32_e32 v97, 0xffff0000, v14
	v_lshlrev_b32_e32 v93, 16, v15
	v_lshlrev_b32_e32 v92, 16, v31
	v_and_b32_e32 v15, 0xffff0000, v15
	v_and_b32_e32 v14, 0xffff0000, v31
	v_lshlrev_b32_e32 v167, 16, v21
	v_add_f32_e32 v191, -1.0, v164
	v_add_f32_e32 v176, -1.0, v166
	v_mov_b32_e32 v208, v165
	v_mov_b32_e32 v209, v37
	v_pk_mul_f32 v[36:37], v[16:17], v[212:213]
	v_mul_f32_e32 v118, v94, v147
	v_mul_f32_e32 v120, v95, v147
	v_mul_f32_e32 v122, v96, v147
	v_lshlrev_b32_e32 v102, 16, v30
	v_and_b32_e32 v96, 0xffff0000, v30
	v_add_f32_e32 v31, -1.0, v14
	v_mov_b32_e32 v30, v3
	v_mov_b32_e32 v94, v15
	s_waitcnt vmcnt(8)
	v_mov_b32_e32 v95, v63
	v_add_f32_e32 v3, -1.0, v92
	v_mov_b32_e32 v126, v93
	v_mov_b32_e32 v127, v62
	v_and_b32_e32 v21, 0xffff0000, v21
	v_and_b32_e32 v20, 0xffff0000, v25
	v_lshlrev_b32_e32 v24, 16, v26
	v_mov_b32_e32 v192, v19
	v_mov_b32_e32 v19, v176
	v_mov_b32_e32 v206, v167
	v_mov_b32_e32 v207, v38
	v_pk_mul_f32 v[210:211], v[190:191], v[208:209]
	v_mul_f32_e32 v91, v36, v36
	v_lshlrev_b32_e32 v80, 16, v29
	v_mul_f32_e32 v108, v100, v147
	v_mul_f32_e32 v104, v101, v147
	v_pk_mul_f32 v[100:101], v[30:31], v[94:95]
	v_pk_mul_f32 v[62:63], v[2:3], v[126:127]
	v_lshlrev_b32_e32 v25, 16, v22
	v_add_f32_e32 v193, -1.0, v20
	v_add_f32_e32 v178, -1.0, v24
	v_mov_b32_e32 v202, v21
	v_mov_b32_e32 v203, v39
	v_pk_mul_f32 v[38:39], v[18:19], v[206:207]
	v_fmac_f32_e32 v91, v210, v210
	v_lshlrev_b32_e32 v81, 16, v13
	v_and_b32_e32 v107, 0xffff0000, v13
	v_and_b32_e32 v106, 0xffff0000, v29
	v_add_f32_e32 v13, -1.0, v80
	v_add_f32_e32 v29, -1.0, v102
	v_mov_b32_e32 v132, v62
	v_mov_b32_e32 v133, v100
	v_and_b32_e32 v169, 0xffff0000, v22
	v_and_b32_e32 v168, 0xffff0000, v26
	v_mov_b32_e32 v194, v9
	v_mov_b32_e32 v9, v178
	v_mov_b32_e32 v200, v25
	v_mov_b32_e32 v201, v32
	v_pk_mul_f32 v[204:205], v[192:193], v[202:203]
	v_fmac_f32_e32 v91, v38, v38
	v_and_b32_e32 v83, 0xffff0000, v12
	v_and_b32_e32 v82, 0xffff0000, v28
	v_add_f32_e32 v129, -1.0, v96
	v_pk_mul_f32 v[148:149], v[132:133], v[132:133]
	v_mov_b32_e32 v128, v1
	v_mov_b32_e32 v132, v97
	v_mov_b32_e32 v133, v61
	v_mov_b32_e32 v1, v29
	v_mov_b32_e32 v136, v103
	v_mov_b32_e32 v137, v60
	v_mov_b32_e32 v130, v7
	v_mov_b32_e32 v7, v13
	v_lshlrev_b32_e32 v13, 16, v12
	v_lshlrev_b32_e32 v12, 16, v28
	v_lshlrev_b32_e32 v171, 16, v23
	v_lshlrev_b32_e32 v170, 16, v27
	v_add_f32_e32 v195, -1.0, v168
	v_mov_b32_e32 v196, v169
	v_mov_b32_e32 v197, v33
	v_pk_mul_f32 v[32:33], v[8:9], v[200:201]
	v_fmac_f32_e32 v91, v204, v204
	v_add_f32_e32 v113, -1.0, v82
	v_pk_mul_f32 v[134:135], v[128:129], v[132:133]
	v_pk_mul_f32 v[60:61], v[0:1], v[136:137]
	v_mov_b32_e32 v112, v5
	v_mov_b32_e32 v156, v83
	v_mov_b32_e32 v157, v57
	v_add_f32_e32 v5, -1.0, v12
	v_mov_b32_e32 v28, v13
	v_mov_b32_e32 v29, v56
	v_add_f32_e32 v173, -1.0, v170
	v_mov_b32_e32 v172, v10
	v_mov_b32_e32 v174, v171
	v_mov_b32_e32 v175, v34
	v_and_b32_e32 v23, 0xffff0000, v23
	v_and_b32_e32 v22, 0xffff0000, v27
	v_pk_mul_f32 v[198:199], v[194:195], v[196:197]
	v_fmac_f32_e32 v91, v32, v32
	v_mov_b32_e32 v138, v60
	v_mov_b32_e32 v139, v134
	v_pk_mul_f32 v[158:159], v[112:113], v[156:157]
	v_pk_mul_f32 v[56:57], v[4:5], v[28:29]
	v_pk_mul_f32 v[188:189], v[172:173], v[174:175]
	v_add_f32_e32 v27, -1.0, v22
	v_mov_b32_e32 v26, v11
	v_mov_b32_e32 v34, v23
	v_fmac_f32_e32 v91, v198, v198
	v_add_f32_e32 v131, -1.0, v106
	v_pk_mul_f32 v[150:151], v[138:139], v[138:139]
	v_mov_b32_e32 v138, v107
	v_mov_b32_e32 v139, v59
	v_mov_b32_e32 v152, v81
	v_mov_b32_e32 v153, v58
	v_mov_b32_e32 v160, v56
	v_mov_b32_e32 v161, v158
	v_pk_mul_f32 v[10:11], v[26:27], v[34:35]
	v_fmac_f32_e32 v91, v188, v188
	v_pk_mul_f32 v[140:141], v[130:131], v[138:139]
	v_pk_mul_f32 v[58:59], v[6:7], v[152:153]
	v_pk_mul_f32 v[160:161], v[160:161], v[160:161]
	v_fmac_f32_e32 v91, v10, v10
	v_mov_b32_e32 v154, v58
	v_mov_b32_e32 v155, v140
	v_add_f32_e32 v91, v91, v160
	v_pk_mul_f32 v[154:155], v[154:155], v[154:155]
	v_add_f32_e32 v91, v91, v161
	v_add_f32_e32 v91, v91, v154
	v_add_f32_e32 v91, v91, v155
	v_add_f32_e32 v91, v91, v150
	v_add_f32_e32 v91, v91, v151
	v_add_f32_e32 v91, v91, v148
	v_add_f32_e32 v91, v91, v149
	v_pk_fma_f32 v[26:27], v[26:27], v[34:35], s[26:27]
	v_pk_fma_f32 v[16:17], v[16:17], v[212:213], s[26:27]
	v_add_f32_dpp v91, v91, v91 quad_perm:[1,0,3,2] row_mask:0xf bank_mask:0xf bound_ctrl:1
	v_pk_fma_f32 v[18:19], v[18:19], v[206:207], s[26:27]
	v_pk_fma_f32 v[34:35], v[192:193], v[202:203], s[26:27]
	v_add_f32_dpp v91, v91, v91 quad_perm:[2,3,0,1] row_mask:0xf bank_mask:0xf bound_ctrl:1
	v_max_f32_e32 v91, 0x179abe15, v91
	v_rsq_f32_e32 v178, v91
	v_pk_fma_f32 v[8:9], v[8:9], v[200:201], s[26:27]
	v_pk_fma_f32 v[4:5], v[4:5], v[28:29], s[26:27]
	v_mul_f32_e32 v150, v87, v147
	v_pk_mul_f32 v[10:11], v[10:11], v[178:179]
	v_pk_fma_f32 v[6:7], v[6:7], v[152:153], s[26:27]
	v_mov_b32_e32 v11, v27
	v_pk_mul_f32 v[10:11], v[10:11], v[22:23]
	v_pk_mul_f32 v[22:23], v[36:37], v[178:179]
	v_pk_fma_f32 v[26:27], v[190:191], v[208:209], s[26:27]
	v_mov_b32_e32 v23, v17
	v_pk_mul_f32 v[16:17], v[22:23], v[162:163]
	v_mul_f32_e32 v87, v11, v146
	v_mul_f32_e32 v22, v17, v145
	s_waitcnt vmcnt(4)
	v_fma_f32 v36, v52, v22, 0
	v_pk_mul_f32 v[22:23], v[210:211], v[178:179]
	v_pk_fma_f32 v[0:1], v[0:1], v[136:137], s[26:27]
	v_mov_b32_e32 v23, v27
	v_pk_mul_f32 v[22:23], v[22:23], v[164:165]
	v_mul_f32_e32 v88, v88, v147
	v_mul_f32_e32 v26, v23, v144
	v_fmac_f32_e32 v36, v53, v26
	v_pk_mul_f32 v[26:27], v[38:39], v[178:179]
	v_mul_f32_e32 v148, v89, v147
	v_mov_b32_e32 v27, v19
	v_pk_mul_f32 v[18:19], v[26:27], v[166:167]
	v_pk_fma_f32 v[2:3], v[2:3], v[126:127], s[26:27]
	v_mul_f32_e32 v26, v19, v143
	v_fmac_f32_e32 v36, v54, v26
	v_pk_mul_f32 v[26:27], v[204:205], v[178:179]
	v_mul_f32_e32 v86, v86, v147
	v_mov_b32_e32 v27, v35
	v_pk_mul_f32 v[20:21], v[26:27], v[20:21]
	s_nop 0
	v_mul_f32_e32 v26, v21, v142
	v_fmac_f32_e32 v36, v55, v26
	v_pk_mul_f32 v[26:27], v[32:33], v[178:179]
	v_pk_fma_f32 v[32:33], v[172:173], v[174:175], s[26:27]
	v_mov_b32_e32 v27, v9
	v_pk_mul_f32 v[8:9], v[26:27], v[24:25]
	v_pk_fma_f32 v[26:27], v[194:195], v[196:197], s[26:27]
	v_mul_f32_e32 v24, v9, v125
	v_fmac_f32_e32 v36, v48, v24
	v_pk_mul_f32 v[24:25], v[198:199], v[178:179]
	s_nop 0
	v_mov_b32_e32 v25, v27
	v_pk_mul_f32 v[24:25], v[24:25], v[168:169]
	s_nop 0
	v_mul_f32_e32 v26, v25, v123
	v_fmac_f32_e32 v36, v49, v26
	v_pk_mul_f32 v[26:27], v[188:189], v[178:179]
	s_nop 0
	v_mov_b32_e32 v27, v33
	v_pk_mul_f32 v[26:27], v[26:27], v[170:171]
	s_nop 0
	v_mul_f32_e32 v32, v27, v121
	v_fmac_f32_e32 v36, v50, v32
	v_pk_mul_f32 v[32:33], v[56:57], v[178:179]
	v_fmac_f32_e32 v36, v51, v87
	v_mov_b32_e32 v33, v5
	v_pk_mul_f32 v[4:5], v[32:33], v[12:13]
	s_nop 0
	v_mul_f32_e32 v12, v5, v119
	v_fmac_f32_e32 v36, v44, v12
	v_pk_fma_f32 v[12:13], v[16:17], v[84:85], 0 op_sel_hi:[1,0,0]
	s_nop 0
	v_pk_fma_f32 v[12:13], v[114:115], v[22:23], v[12:13] op_sel_hi:[0,1,1]
	v_pk_fma_f32 v[12:13], v[116:117], v[18:19], v[12:13] op_sel_hi:[0,1,1]
	v_pk_fma_f32 v[12:13], v[118:119], v[20:21], v[12:13] op_sel_hi:[0,1,1]
	v_pk_fma_f32 v[8:9], v[120:121], v[8:9], v[12:13] op_sel_hi:[0,1,1]
	v_pk_fma_f32 v[8:9], v[122:123], v[24:25], v[8:9] op_sel_hi:[0,1,1]
	v_pk_fma_f32 v[8:9], v[124:125], v[26:27], v[8:9] op_sel_hi:[0,1,1]
	v_pk_fma_f32 v[8:9], v[110:111], v[10:11], v[8:9] op_sel_hi:[0,1,1]
	v_pk_fma_f32 v[4:5], v[108:109], v[4:5], v[8:9] op_sel_hi:[0,1,1]
	v_pk_mul_f32 v[8:9], v[158:159], v[178:179]
	v_pk_fma_f32 v[10:11], v[112:113], v[156:157], s[26:27]
	s_nop 0
	v_mov_b32_e32 v9, v11
	v_pk_mul_f32 v[8:9], v[8:9], v[82:83]
	s_nop 0
	v_pk_fma_f32 v[4:5], v[104:105], v[8:9], v[4:5] op_sel_hi:[0,1,1]
	v_mul_f32_e32 v8, v9, v117
	v_fmac_f32_e32 v36, v45, v8
	v_pk_mul_f32 v[8:9], v[58:59], v[178:179]
	s_nop 0
	v_mov_b32_e32 v9, v7
	v_pk_mul_f32 v[6:7], v[8:9], v[80:81]
	v_pk_fma_f32 v[8:9], v[130:131], v[138:139], s[26:27]
	v_pk_fma_f32 v[4:5], v[98:99], v[6:7], v[4:5] op_sel_hi:[0,1,1]
	v_mul_f32_e32 v6, v7, v115
	v_fmac_f32_e32 v36, v46, v6
	v_pk_mul_f32 v[6:7], v[140:141], v[178:179]
	s_nop 0
	v_mov_b32_e32 v7, v9
	v_pk_mul_f32 v[6:7], v[6:7], v[106:107]
	s_nop 0
	v_pk_fma_f32 v[4:5], v[90:91], v[6:7], v[4:5] op_sel_hi:[0,1,1]
	v_mul_f32_e32 v6, v7, v111
	v_fmac_f32_e32 v36, v47, v6
	v_pk_mul_f32 v[6:7], v[60:61], v[178:179]
	s_nop 0
	v_mov_b32_e32 v7, v1
	v_pk_mul_f32 v[0:1], v[6:7], v[102:103]
	v_pk_fma_f32 v[6:7], v[128:129], v[132:133], s[26:27]
	v_pk_fma_f32 v[4:5], v[88:89], v[0:1], v[4:5] op_sel_hi:[0,1,1]
	v_mul_f32_e32 v0, v1, v109
	v_fmac_f32_e32 v36, v40, v0
	v_pk_mul_f32 v[0:1], v[134:135], v[178:179]
	s_nop 0
	v_mov_b32_e32 v1, v7
	v_pk_mul_f32 v[0:1], v[0:1], v[96:97]
	s_nop 0
	v_pk_fma_f32 v[4:5], v[148:149], v[0:1], v[4:5] op_sel_hi:[0,1,1]
	v_mul_f32_e32 v0, v1, v105
	v_fmac_f32_e32 v36, v41, v0
	v_pk_mul_f32 v[0:1], v[62:63], v[178:179]
	s_nop 0
	v_mov_b32_e32 v1, v3
	v_pk_mul_f32 v[0:1], v[0:1], v[92:93]
	s_nop 0
	v_pk_fma_f32 v[2:3], v[86:87], v[0:1], v[4:5] op_sel_hi:[0,1,1]
	v_mul_f32_e32 v0, v1, v99
	v_fmac_f32_e32 v36, v42, v0
	v_pk_mul_f32 v[0:1], v[100:101], v[178:179]
	v_pk_fma_f32 v[4:5], v[30:31], v[94:95], s[26:27]
	s_nop 0
	v_mov_b32_e32 v1, v5
	v_pk_mul_f32 v[0:1], v[0:1], v[14:15]
	v_mov_b32_e32 v5, 0
	v_pk_fma_f32 v[2:3], v[150:151], v[0:1], v[2:3] op_sel_hi:[0,1,1]
	v_mul_f32_e32 v0, v1, v85
	v_fmac_f32_e32 v36, v43, v0
	v_mov_b32_e32 v0, v177
	v_mov_b32_e32 v1, v177
	v_add_f32_dpp v4, v36, v36 quad_perm:[1,0,3,2] row_mask:0xf bank_mask:0xf bound_ctrl:1
	v_mov_b32_dpp v0, v2 quad_perm:[1,0,3,2] row_mask:0xf bank_mask:0xf
	v_mov_b32_dpp v1, v3 quad_perm:[1,0,3,2] row_mask:0xf bank_mask:0xf
	v_pk_add_f32 v[0:1], v[2:3], v[0:1]
	v_mov_b32_e32 v2, 0
	v_mov_b32_e32 v3, 0
	v_mov_b32_dpp v5, v4 quad_perm:[2,3,0,1] row_mask:0xf bank_mask:0xf
	v_mov_b32_dpp v2, v0 quad_perm:[2,3,0,1] row_mask:0xf bank_mask:0xf
	v_mov_b32_dpp v3, v1 quad_perm:[2,3,0,1] row_mask:0xf bank_mask:0xf
	s_and_saveexec_b64 s[0:1], s[2:3]
	s_cbranch_execz .LBB0_513
	v_pk_add_f32 v[8:9], v[0:1], v[2:3]
	v_lshl_add_u64 v[6:7], s[66:67], 0, v[74:75]
	v_add_f32_e32 v3, v4, v5
	v_mov_b32_e32 v0, v178
	v_mov_b32_e32 v1, v8
	v_mov_b32_e32 v2, v9
	global_store_dwordx4 v[6:7], v[0:3], off
	s_branch .LBB0_513
